# attention (MLA and SWA): XOR swizzle of the transposed V tile in LDS so the stash's 2-byte writes are bank-conflict free; readers use quad^2 bases / swapped half offsets
# baseline (speedup 1.0000x reference)
; template <bool MLA>
; __device__ __forceinline__ void attn_phase(const Args& a, LAS unsigned char* lds) {
;     ...
;         auto fetch = [&](int kt) {
;             pk0 = (u32x4){0u, 0u, 0u, 0u}; pk1 = pk0; pv = pk0;
;             if (MLA) {
;                 { const int j = tid / 12, ch = tid % 12; const int kk = kt * 64 + j; const size_t kr = krow0 + kk;
;                   if (!samp || kk < 1056) pk0 = ch < 8 ? *(const u32x4*)(KVg + kr * 2048 + h * 128 + ch * 8) : *(const u32x4*)(KRg + kr * 32 + (ch - 8) * 8); }
;                 if (tid < 256) { const int idx = tid + 512; const int j = idx / 12, ch = idx % 12; const int kk = kt * 64 + j; const size_t kr = krow0 + kk;
;                   if (!samp || kk < 1056) pk1 = ch < 8 ? *(const u32x4*)(KVg + kr * 2048 + h * 128 + ch * 8) : *(const u32x4*)(KRg + kr * 32 + (ch - 8) * 8); }
;                 { const int j = tid >> 3, ec = tid & 7; const int kk = kt * 64 + j; const size_t kr = krow0 + kk;
;                   if (!samp || kk < 1056) pv = *(const u32x4*)(KVg + kr * 2048 + h * 128 + 64 + ec * 8); }
;             } else {
;                 const int j = tid >> 3, ch = tid & 7; const int kk = kt * 64 + j;
;                 if (!samp) { const size_t kr = (size_t)b * 2048 + (size_t)(cch - 2 + kt) * 64 + j;
;                     pk0 = *(const u32x4*)(SP + kr * 1536 + 1024 + kvh * 64 + ch * 8); pv = *(const u32x4*)(SP + kr * 1536 + 1280 + kvh * 64 + ch * 8); }
;                 else if (kk < 128) { pk0 = *(const u32x4*)(KC + ((size_t)b * 128 + kk) * 256 + kvh * 64 + ch * 8); pv = *(const u32x4*)(VC + ((size_t)b * 128 + kk) * 256 + kvh * 64 + ch * 8); }
;                 else if (kk < 160) { const size_t kr = (size_t)NTP + b * 32 + (kk - 128);
;                     pk0 = *(const u32x4*)(SP + kr * 1536 + 1024 + kvh * 64 + ch * 8); pv = *(const u32x4*)(SP + kr * 1536 + 1280 + kvh * 64 + ch * 8); }
;             }
;         };
;         auto stash = [&](int par) {
;             LAS bf16_t* Ks = KsB + par * KVB; LAS bf16_t* VTs = Ks + 64 * QST;
;             if (MLA) {
;                 { const int j = tid / 12, ch = tid % 12; *(LAS u32x4*)(Ks + j * QST + ch * 8) = pk0; }
;                 if (tid < 256) { const int idx = tid + 512; const int j = idx / 12, ch = idx % 12; *(LAS u32x4*)(Ks + j * QST + ch * 8) = pk1; }
;             } else { const int j = tid >> 3, ch = tid & 7; *(LAS u32x4*)(Ks + j * QST + ch * 8) = pk0; }
.LBB0_439:
	s_or_b64 exec, exec, s[0:1]
	v_mov_b32_e32 v107, v187
	s_mov_b32 s33, s69
	s_waitcnt lgkmcnt(0)
	s_barrier
	s_cmpk_gt_i32 s33, 0x10ff
	v_readfirstlane_b32 s0, v107
	s_cbranch_scc1 .LBB0_509
	s_ashr_i32 s0, s0, 1
	v_and_b32_e32 v3, 15, v107
	s_and_b32 s61, s0, 0xffffffc0
	s_andn2_b32 s0, s0, 31
	v_or_b32_e32 v88, s0, v3
	s_movk_i32 s0, 0x800
	v_lshlrev_b32_e32 v157, 3, v107
	v_cmp_gt_i32_e64 s[36:37], s0, v107
	v_and_b32_e32 v2, 8, v157
	v_readlane_b32 s0, v252, 18
	v_ashrrev_i32_e32 v156, 1, v107
	v_lshlrev_b32_e32 v0, 3, v2
	v_readlane_b32 s1, v252, 19
	s_movk_i32 s4, 0xd0
	v_lshlrev_b32_e32 v5, 1, v2
	v_lshl_add_u64 v[90:91], s[0:1], 0, v[0:1]
	v_mul_lo_u32 v0, v156, s4
	s_mov_b32 s1, 0x2aaaaaab
	v_add3_u32 v158, 0, v0, v5
	v_mul_hi_i32 v0, v107, s1
	v_lshrrev_b32_e32 v5, 31, v0
	v_ashrrev_i32_e32 v0, 1, v0
	v_add_u32_e32 v92, v0, v5
	v_mul_lo_u32 v0, v92, 12
	v_sub_u32_e32 v5, v107, v0
	v_readlane_b32 s2, v253, 14
	v_lshlrev_b32_e32 v0, 3, v5
	v_readlane_b32 s3, v253, 15
	v_ashrrev_i32_e32 v97, 31, v0
	v_mov_b32_e32 v96, v0
	v_lshl_add_u64 v[94:95], v[0:1], 1, s[2:3]
	v_add_u32_e32 v0, 0x200, v107
	v_mul_hi_i32 v6, v0, s1
	v_lshrrev_b32_e32 v7, 31, v6
	v_ashrrev_i32_e32 v6, 1, v6
	v_add_u32_e32 v98, v6, v7
	s_movk_i32 s0, 0x317f
	v_mul_lo_u32 v6, v98, 12
	v_cmp_lt_i32_e64 s[38:39], s0, v107
	s_movk_i32 s0, 0x100
	v_sub_u32_e32 v6, v0, v6
	v_cmp_gt_i32_e64 s[44:45], s0, v107
	v_lshlrev_b32_e32 v0, 3, v6
	v_ashrrev_i32_e32 v104, 3, v107
	s_movk_i32 s0, 0x41f
	v_and_b32_e32 v106, 56, v157
	v_lshl_add_u64 v[100:101], v[0:1], 1, s[2:3]
	v_ashrrev_i32_e32 v103, 31, v0
	v_mov_b32_e32 v102, v0
	v_cmp_lt_i32_e64 s[50:51], s0, v104
	v_mul_u32_u24_e32 v163, 0x88, v106
	v_and_b32_e32 v0, 6, v187
	v_lshlrev_b32_e32 v0, 2, v0
	v_xor_b32_e32 v0, v0, v104
	v_lshlrev_b32_e32 v0, 1, v0
	v_readlane_b32 s0, v254, 22
	v_bfe_u32 v4, v107, 4, 2
	v_mul_lo_u32 v159, v92, s4
	v_add3_u32 v164, s0, v163, v0
	v_xor_b32_e32 v0, 16, v234
	v_cmp_lt_i32_e32 vcc, v0, v235
	s_movk_i32 s0, 0x2e7f
	v_cmp_lt_i32_e64 s[52:53], s0, v107
	v_cndmask_b32_e32 v0, v234, v0, vcc
	v_lshlrev_b32_e32 v167, 2, v0
	v_xor_b32_e32 v0, 32, v234
	s_movk_i32 s0, 0x3df
	v_cmp_lt_i32_e32 vcc, v0, v235
	v_mul_lo_u32 v161, v98, s4
	v_cmp_lt_i32_e64 s[54:55], s0, v104
	v_readlane_b32 s2, v253, 24
	v_lshlrev_b32_e32 v165, 4, v4
	v_cndmask_b32_e32 v0, v234, v0, vcc
	v_readlane_b32 s0, v252, 20
	v_cmp_gt_i32_e64 s[40:41], 8, v5
	v_cmp_lt_i32_e64 s[42:43], 7, v5
	v_cmp_gt_i32_e64 s[46:47], 8, v6
	v_cmp_lt_i32_e64 s[48:49], 7, v6
	v_add_u32_e32 v7, 0, v159
	v_lshlrev_b32_e32 v160, 4, v5
	v_add_u32_e32 v5, 0, v161
	v_lshlrev_b32_e32 v162, 4, v6
	v_add_u32_e32 v108, 64, v92
	v_add_u32_e32 v110, 64, v98
	v_add_u32_e32 v112, 64, v104
	v_readlane_b32 s3, v253, 25
	v_add_u32_e32 v6, 0, v165
	v_lshlrev_b32_e32 v166, 2, v4
	v_lshlrev_b32_e32 v118, 3, v4
	v_lshlrev_b32_e32 v168, 2, v0
	v_mov_b32_e32 v119, v1
	v_readlane_b32 s1, v252, 21
	v_or_b32_e32 v122, 16, v88
	v_mul_lo_u32 v4, v88, s4
	v_lshlrev_b32_e32 v0, 1, v106
	s_add_i32 s61, s61, 64
	v_ashrrev_i32_e32 v93, 31, v92
	v_ashrrev_i32_e32 v99, 31, v98
	v_ashrrev_i32_e32 v105, 31, v104
	v_ashrrev_i32_e32 v109, 31, v108
	v_ashrrev_i32_e32 v111, 31, v110
	v_ashrrev_i32_e32 v113, 31, v112
	v_lshl_add_u64 v[114:115], v[96:97], 1, s[2:3]
	v_lshl_add_u64 v[116:117], v[102:103], 1, s[2:3]
	v_lshl_add_u64 v[120:121], s[0:1], 0, v[118:119]
	v_mul_u32_u24_e32 v119, 0xd0, v3
	v_mul_u32_u24_e32 v169, 0x88, v3
	v_ashrrev_i32_e32 v89, 31, v88
	v_ashrrev_i32_e32 v123, 31, v122
	v_lshl_add_u64 v[124:125], s[2:3], 0, v[0:1]
	v_lshlrev_b32_e32 v126, 1, v2
	v_add_u32_e32 v170, v7, v160
	v_add_u32_e32 v171, v5, v162
	v_add_u32_e32 v172, v6, v4
	s_branch .LBB0_442

; #define LAS __attribute__((address_space(3)))
; template <bool MLA>
; __device__ __forceinline__ void attn_phase(const Args& a, LAS unsigned char* lds) {
;     ...
;         auto stash = [&](int par) {
;             LAS bf16_t* Ks = KsB + par * KVB; LAS bf16_t* VTs = Ks + 64 * QST;
;             if (MLA) {
;                 { const int j = tid / 12, ch = tid % 12; *(LAS u32x4*)(Ks + j * QST + ch * 8) = pk0; }
;                 if (tid < 256) { const int idx = tid + 512; const int j = idx / 12, ch = idx % 12; *(LAS u32x4*)(Ks + j * QST + ch * 8) = pk1; }
;             } else { const int j = tid >> 3, ch = tid & 7; *(LAS u32x4*)(Ks + j * QST + ch * 8) = pk0; }
;             { const int j = tid >> 3, ec = tid & 7; const unsigned vv[4] = {pv.x, pv.y, pv.z, pv.w};
; #pragma unroll
;               for (int k = 0; k < 4; ++k) { VTs[(ec * 8 + 2 * k) * 68 + j] = (bf16_t)(vv[k] & 0xFFFFu); VTs[(ec * 8 + 2 * k + 1) * 68 + j] = (bf16_t)(vv[k] >> 16); } }
;         };
;         fetch(kt0);
;         stash(0);
;         if (kt0 + 1 < kt1) fetch(kt0 + 1);
; #pragma unroll 1
;         for (int kt = kt0; kt < kt1; ++kt) {
;             __syncthreads();
;             if (kt + 1 < kt1) { stash((kt + 1 - kt0) & 1); if (kt + 2 < kt1) fetch(kt + 2); }
.LBB0_482:
	s_add_i32 s67, s6, 1
	s_cmp_ge_i32 s67, s63
	s_waitcnt lgkmcnt(0)
	s_barrier
	s_cbranch_scc1 .LBB0_495
	s_bitcmp1_b32 s67, 0
	s_cselect_b32 s0, 0x5600, 0
	s_add_i32 s2, s0, 0
	v_add3_u32 v0, s2, v159, v160
	s_waitcnt vmcnt(0)
	ds_write_b128 v0, v[28:31] offset:53248
	s_and_saveexec_b64 s[0:1], s[44:45]
	v_add3_u32 v0, s2, v161, v162
	ds_write_b128 v0, v[32:35] offset:53248
	s_or_b64 exec, exec, s[0:1]
	s_add_i32 s2, s2, 0xd000
	v_and_b32_e32 v0, 6, v187
	v_lshlrev_b32_e32 v0, 2, v0
	v_xor_b32_e32 v0, v0, v104
	v_lshlrev_b32_e32 v0, 1, v0
	s_add_i32 s0, s6, 2
	v_add3_u32 v0, s2, v163, v0
	s_cmp_ge_i32 s0, s63
	ds_write_b16 v0, v36 offset:13312
	ds_write_b16_d16_hi v0, v36 offset:13448
	ds_write_b16 v0, v37 offset:13584
	ds_write_b16_d16_hi v0, v37 offset:13720
	ds_write_b16 v0, v38 offset:13856
	ds_write_b16_d16_hi v0, v38 offset:13992
	ds_write_b16 v0, v39 offset:14128
	ds_write_b16_d16_hi v0, v39 offset:14264
	s_cbranch_scc1 .LBB0_495
	v_add3_u32 v2, v92, s66, 64
	v_mov_b32_e32 v32, 0
	v_mov_b32_e32 v33, v1
	v_cmp_gt_i32_e32 vcc, s58, v2
	s_xor_b64 s[0:1], s[34:35], -1
	v_mov_b32_e32 v34, v1
	v_mov_b32_e32 v35, v1
	v_mov_b64_e32 v[28:29], v[32:33]
	s_or_b64 s[4:5], s[0:1], vcc
	v_mov_b64_e32 v[30:31], v[34:35]
	s_and_saveexec_b64 s[2:3], s[4:5]
	s_cbranch_execz .LBB0_488
	v_ashrrev_i32_e32 v3, 31, v2
	v_lshl_add_u64 v[2:3], s[56:57], 0, v[2:3]
	v_lshlrev_b64 v[28:29], 12, v[2:3]
	v_lshlrev_b64 v[2:3], 6, v[2:3]
	s_movk_i32 s4, 0xff80
	v_lshl_add_u64 v[2:3], v[94:95], 0, v[2:3]
	s_mov_b32 s5, -1
	v_lshl_add_u64 v[28:29], v[128:129], 0, v[28:29]
	v_lshl_add_u64 v[2:3], v[2:3], 0, s[4:5]
	v_cndmask_b32_e64 v3, v3, v29, s[40:41]
	v_cndmask_b32_e64 v2, v2, v28, s[40:41]
	global_load_dwordx4 v[28:31], v[2:3], off

; template <bool MLA>
; __device__ __forceinline__ void attn_phase(const Args& a, LAS unsigned char* lds) {
;     ...
;                 float mx = -INFINITY;
; #pragma unroll
;                 for (int sub = 0; sub < 4; ++sub) mx = fmaxf(fmaxf(fmaxf(mx, sv[sub][0]), fmaxf(sv[sub][1], sv[sub][2])), sv[sub][3]);
;                 mx = fmaxf(mx, __shfl_xor(mx, 16)); mx = fmaxf(mx, __shfl_xor(mx, 32));
;                 const float mn = fmaxf(m[g], mx), alpha = __builtin_amdgcn_exp2f(m[g] - mn); m[g] = mn;
;                 f32x4 ps4 = (f32x4){0.f, 0.f, 0.f, 0.f};
; #pragma unroll
;                 for (int sub = 0; sub < 4; ++sub) {
;                     const f32x4 d = sv[sub] - mn;
;                     const f32x4 pe = (f32x4){__builtin_amdgcn_exp2f(d[0]), __builtin_amdgcn_exp2f(d[1]), __builtin_amdgcn_exp2f(d[2]), __builtin_amdgcn_exp2f(d[3])};
;                     s[g][sub] = pe; ps4 += pe;
;                 }
;                 lsum[g] = lsum[g] * alpha + ((ps4[0] + ps4[1]) + (ps4[2] + ps4[3]));
.LBB0_501:
	s_waitcnt lgkmcnt(0)
	v_max3_f32 v0, v175, v206, v207
	v_sub_f32_e32 v74, v155, v0
	v_sub_f32_e32 v75, v154, v0
	v_sub_f32_e32 v72, v153, v0
	v_sub_f32_e32 v73, v152, v0
	v_exp_f32_e32 v152, v75
	v_exp_f32_e32 v153, v74
	v_sub_f32_e32 v78, v148, v0
	v_sub_f32_e32 v79, v151, v0
	v_sub_f32_e32 v148, v150, v0
	v_sub_f32_e32 v77, v149, v0
	v_exp_f32_e32 v148, v148
	v_exp_f32_e32 v149, v79
	v_exp_f32_e32 v150, v78
	v_sub_f32_e32 v78, v144, v0
	v_sub_f32_e32 v79, v147, v0
	v_sub_f32_e32 v144, v146, v0
	v_sub_f32_e32 v76, v175, v0
	v_exp_f32_e32 v151, v77
	v_sub_f32_e32 v77, v145, v0
	v_exp_f32_e32 v144, v144
	v_exp_f32_e32 v145, v79
	v_exp_f32_e32 v146, v78
	v_sub_f32_e32 v78, v140, v0
	v_sub_f32_e32 v79, v143, v0
	v_sub_f32_e32 v140, v142, v0
	v_exp_f32_e32 v142, v140
	v_exp_f32_e32 v143, v79
	v_exp_f32_e32 v178, v76
	v_exp_f32_e32 v154, v73
	v_exp_f32_e32 v155, v72
	v_pk_add_f32 v[72:73], v[152:153], 0 op_sel_hi:[1,0]
	v_exp_f32_e32 v147, v77
	v_pk_add_f32 v[72:73], v[148:149], v[72:73]
	v_sub_f32_e32 v77, v141, v0
	v_pk_add_f32 v[72:73], v[144:145], v[72:73]
	v_exp_f32_e32 v176, v78
	v_pk_add_f32 v[72:73], v[142:143], v[72:73]
	v_pk_mul_f32 v[78:79], v[58:59], v[178:179] op_sel_hi:[1,0]
	v_pk_mul_f32 v[58:59], v[70:71], v[178:179] op_sel_hi:[1,0]
	v_cvt_pk_bf16_f32 v70, v142, v143
	v_max3_f32 v141, v136, v139, v138
	v_max3_f32 v142, v86, v81, v80
	v_max3_f32 v141, v141, v134, v85
	v_max3_f32 v142, v142, v2, v83
	v_max3_f32 v141, v141, v137, v84
	v_max3_f32 v142, v142, v87, v82
	s_mov_b32 s0, 0xff800000
	v_max_f32_e32 v141, v141, v135
	v_max3_f32 v141, v141, v142, v3
	ds_bpermute_b32 v142, v167, v141
	v_pk_add_f32 v[74:75], v[154:155], 0 op_sel_hi:[1,0]
	v_exp_f32_e32 v177, v77
	v_pk_add_f32 v[74:75], v[150:151], v[74:75]
	v_pk_mul_f32 v[76:77], v[56:57], v[178:179] op_sel_hi:[1,0]
	s_waitcnt lgkmcnt(0)
	v_max_f32_e32 v141, v141, v142
	ds_bpermute_b32 v142, v168, v141
	v_pk_add_f32 v[74:75], v[146:147], v[74:75]
	v_pk_mul_f32 v[56:57], v[68:69], v[178:179] op_sel_hi:[1,0]
	v_cvt_pk_bf16_f32 v69, v146, v147
	v_cvt_pk_bf16_f32 v68, v144, v145
	s_waitcnt lgkmcnt(0)
; #define LAS __attribute__((address_space(3)))
; __device__ __forceinline__ unsigned pk2(float lo, float hi) { const f32x2 v = {lo, hi}; const bf16v2_t b = __builtin_convertvector(v, bf16v2_t); return __builtin_bit_cast(unsigned, b); }
; template <bool MLA>
; __device__ __forceinline__ void attn_phase(const Args& a, LAS unsigned char* lds) {
;     ...
;                 lsum[g] = lsum[g] * alpha + ((ps4[0] + ps4[1]) + (ps4[2] + ps4[3]));
; #pragma unroll
;                 for (int et = 0; et < 4; ++et) O[g][et] *= alpha;
; #pragma unroll
;                 for (int s2 = 0; s2 < 2; ++s2) {
;                     const unsigned a0 = pk2(s[g][2 * s2][0], s[g][2 * s2][1]), a1 = pk2(s[g][2 * s2][2], s[g][2 * s2][3]), a2 = pk2(s[g][2 * s2 + 1][0], s[g][2 * s2 + 1][1]), a3 = pk2(s[g][2 * s2 + 1][2], s[g][2 * s2 + 1][3]);
;                     const u32x4 pu = (u32x4){a0, a1, a2, a3}; pf[g][s2] = *(const bf16x8*)&pu;
;                 }
;             }
; #pragma unroll
;             for (int s2 = 0; s2 < 2; ++s2)
; #pragma unroll
;                 for (int et = 0; et < 4; ++et) {
;                     const LAS bf16_t* vp = VTs + (et * 16 + r) * 68 + s2 * 32 + quad * 4;
;                     const u32x2 v0 = *(const LAS u32x2*)vp, v1 = *(const LAS u32x2*)(vp + 16);
;                     const u32x4 vu = (u32x4){v0.x, v0.y, v1.x, v1.y};
;                     O[0][et] = __builtin_amdgcn_mfma_f32_16x16x32_bf16(*(const bf16x8*)&vu, pf[0][s2], O[0][et], 0, 0, 0);
;                     O[1][et] = __builtin_amdgcn_mfma_f32_16x16x32_bf16(*(const bf16x8*)&vu, pf[1][s2], O[1][et], 0, 0, 0);
;                 }
	v_max3_f32 v141, v173, v141, v142
	v_xor_b32_e32 v247, 16, v118
	v_add3_u32 v232, s68, v118, v169
	v_add3_u32 v247, s68, v247, v169
	v_add_u32_e32 v233, 0x10000, v232
	v_add_u32_e32 v239, 0x10800, v247
	v_add_u32_e32 v240, 0x11000, v232
	v_add_u32_e32 v246, 0x11800, v247
	ds_read2_b64 v[208:211], v233 offset0:128 offset1:132
	ds_read2_b64 v[212:215], v239 offset0:144 offset1:148
	ds_read2_b64 v[216:219], v240 offset0:164 offset1:160
	ds_read2_b64 v[220:223], v246 offset0:180 offset1:176
	ds_read2_b64 v[224:227], v239 offset0:152 offset1:156
	ds_read2_b64 v[228:231], v240 offset0:172 offset1:168
	v_sub_f32_e32 v142, v137, v141
	v_sub_f32_e32 v143, v136, v141
	v_sub_f32_e32 v137, v139, v141
	v_sub_f32_e32 v136, v138, v141
	v_exp_f32_e32 v138, v143
	v_exp_f32_e32 v139, v142
	v_sub_f32_e32 v147, v135, v141
	v_sub_f32_e32 v146, v134, v141
	v_exp_f32_e32 v146, v146
	v_exp_f32_e32 v147, v147
	v_exp_f32_e32 v136, v136
	v_exp_f32_e32 v137, v137
	v_sub_f32_e32 v85, v85, v141
	v_sub_f32_e32 v84, v84, v141
	v_pk_add_f32 v[144:145], v[138:139], 0 op_sel_hi:[1,0]
	v_exp_f32_e32 v134, v84
	v_exp_f32_e32 v135, v85
	v_sub_f32_e32 v81, v81, v141
	v_sub_f32_e32 v80, v80, v141
	v_pk_add_f32 v[84:85], v[146:147], v[144:145]
	v_exp_f32_e32 v144, v80
	v_exp_f32_e32 v145, v81
	v_pk_add_f32 v[74:75], v[176:177], v[74:75]
	v_pk_add_f32 v[142:143], v[136:137], 0 op_sel_hi:[1,0]
	v_sub_f32_e32 v87, v87, v141
	v_sub_f32_e32 v86, v86, v141
	v_add_f32_e32 v72, v72, v73
	v_add_f32_e32 v73, v74, v75
	v_pk_mul_f32 v[74:75], v[62:63], v[178:179] op_sel_hi:[1,0]
	v_cvt_pk_bf16_f32 v62, v148, v149
	v_pk_add_f32 v[142:143], v[134:135], v[142:143]
	v_exp_f32_e32 v148, v86
	v_exp_f32_e32 v149, v87
	v_sub_f32_e32 v86, v3, v141
	v_sub_f32_e32 v87, v2, v141
	v_sub_f32_e32 v3, v83, v141
	v_sub_f32_e32 v2, v82, v141
	v_pk_add_f32 v[80:81], v[144:145], v[142:143]
	v_exp_f32_e32 v2, v2
	v_exp_f32_e32 v3, v3
	v_exp_f32_e32 v142, v87
	v_exp_f32_e32 v143, v86
	v_cvt_pk_bf16_f32 v63, v150, v151
	v_sub_f32_e32 v150, v173, v141
	v_pk_add_f32 v[84:85], v[148:149], v[84:85]
	v_pk_add_f32 v[80:81], v[2:3], v[80:81]
	v_pk_add_f32 v[82:83], v[142:143], v[84:85]
	v_exp_f32_e32 v150, v150
	v_pk_mov_b32 v[84:85], v[80:81], v[82:83] op_sel:[1,0]
	v_mov_b32_e32 v81, v83
	v_pk_add_f32 v[80:81], v[84:85], v[80:81]
	s_add_i32 s68, s68, 0xd000
	v_add_f32_e32 v151, v80, v81
	v_fmac_f32_e32 v151, v127, v150
	v_pk_mul_f32 v[82:83], v[42:43], v[150:151] op_sel_hi:[1,0]
	v_pk_mul_f32 v[42:43], v[54:55], v[150:151] op_sel_hi:[1,0]
	v_cvt_pk_bf16_f32 v54, v2, v3
	v_add3_u32 v2, s68, v118, v169
	v_add_u32_e32 v3, 0x3000, v2
	v_pk_mul_f32 v[86:87], v[46:47], v[150:151] op_sel_hi:[1,0]
	v_pk_mul_f32 v[84:85], v[44:45], v[150:151] op_sel_hi:[1,0]
	v_cvt_pk_bf16_f32 v44, v136, v137
	v_cvt_pk_bf16_f32 v46, v134, v135
	v_add_f32_e32 v140, v72, v73
	v_pk_mul_f32 v[72:73], v[60:61], v[178:179] op_sel_hi:[1,0]
	v_cvt_pk_bf16_f32 v60, v152, v153
	v_cvt_pk_bf16_f32 v61, v154, v155
	v_pk_mul_f32 v[80:81], v[40:41], v[150:151] op_sel_hi:[1,0]
	v_cvt_pk_bf16_f32 v45, v138, v139
	v_cvt_pk_bf16_f32 v47, v146, v147
	v_add_u32_e32 v127, 0x3800, v2
	s_waitcnt lgkmcnt(0)
	v_mfma_f32_16x16x32_bf16 v[76:79], v[208:211], v[60:63], v[76:79]
	v_add_u32_e32 v138, 0x4000, v2
	v_pk_mul_f32 v[66:67], v[66:67], v[178:179] op_sel_hi:[1,0]
	v_pk_mul_f32 v[64:65], v[64:65], v[178:179] op_sel_hi:[1,0]
	v_mfma_f32_16x16x32_bf16 v[80:83], v[208:211], v[44:47], v[80:83]
	v_pk_mul_f32 v[50:51], v[50:51], v[150:151] op_sel_hi:[1,0]
	v_pk_mul_f32 v[48:49], v[48:49], v[150:151] op_sel_hi:[1,0]
	v_mfma_f32_16x16x32_bf16 v[72:75], v[212:215], v[60:63], v[72:75]
	v_add_u32_e32 v2, 0x4800, v2
	v_pk_mul_f32 v[40:41], v[52:53], v[150:151] op_sel_hi:[1,0]
	v_cvt_pk_bf16_f32 v52, v144, v145
	v_mfma_f32_16x16x32_bf16 v[84:87], v[212:215], v[44:47], v[84:87]
	v_cvt_pk_bf16_f32 v55, v142, v143
	v_cvt_pk_bf16_f32 v71, v176, v177
	v_mfma_f32_16x16x32_bf16 v[64:67], v[216:219], v[60:63], v[64:67]
	v_cvt_pk_bf16_f32 v53, v148, v149
	v_fmac_f32_e32 v140, v174, v178
	v_mov_b32_e32 v173, v141
	v_mfma_f32_16x16x32_bf16 v[48:51], v[216:219], v[44:47], v[48:51]
	v_mov_b32_e32 v175, v0
	v_mov_b32_e32 v174, v140
	v_mfma_f32_16x16x32_bf16 v[142:145], v[220:223], v[60:63], v[56:59]
	s_movk_i32 s58, 0x420
	v_mfma_f32_16x16x32_bf16 v[134:137], v[220:223], v[44:47], v[40:43]
	v_mov_b32_e32 v127, v151
	v_mfma_f32_16x16x32_bf16 v[60:63], v[224:227], v[68:71], v[72:75]
	s_nop 2
	ds_read2_b64 v[40:43], v3 offset0:136 offset1:140
	ds_read2_b64 v[72:75], v246 offset0:188 offset1:184
	v_mfma_f32_16x16x32_bf16 v[64:67], v[228:231], v[68:71], v[64:67]
	v_mfma_f32_16x16x32_bf16 v[48:51], v[228:231], v[52:55], v[48:51]
	s_waitcnt lgkmcnt(1)
	v_mfma_f32_16x16x32_bf16 v[56:59], v[40:43], v[68:71], v[76:79]
	v_mfma_f32_16x16x32_bf16 v[40:43], v[40:43], v[52:55], v[80:83]
	v_mfma_f32_16x16x32_bf16 v[44:47], v[224:227], v[52:55], v[84:87]
	s_waitcnt lgkmcnt(0)
	v_mfma_f32_16x16x32_bf16 v[68:71], v[72:75], v[68:71], v[142:145]
	v_mfma_f32_16x16x32_bf16 v[52:55], v[72:75], v[52:55], v[134:137]
	s_add_i32 s66, s66, 64
	s_cmp_eq_u32 s63, s67
	s_cbranch_scc0 .LBB0_504
	s_branch .LBB0_505

; template <bool MLA>
; __device__ __forceinline__ void attn_phase(const Args& a, LAS unsigned char* lds) {
;     ...
;         auto fetch = [&](int kt) {
;             pk0 = (u32x4){0u, 0u, 0u, 0u}; pk1 = pk0; pv = pk0;
;             if (MLA) {
;                 { const int j = tid / 12, ch = tid % 12; const int kk = kt * 64 + j; const size_t kr = krow0 + kk;
;                   if (!samp || kk < 1056) pk0 = ch < 8 ? *(const u32x4*)(KVg + kr * 2048 + h * 128 + ch * 8) : *(const u32x4*)(KRg + kr * 32 + (ch - 8) * 8); }
;                 if (tid < 256) { const int idx = tid + 512; const int j = idx / 12, ch = idx % 12; const int kk = kt * 64 + j; const size_t kr = krow0 + kk;
;                   if (!samp || kk < 1056) pk1 = ch < 8 ? *(const u32x4*)(KVg + kr * 2048 + h * 128 + ch * 8) : *(const u32x4*)(KRg + kr * 32 + (ch - 8) * 8); }
;                 { const int j = tid >> 3, ec = tid & 7; const int kk = kt * 64 + j; const size_t kr = krow0 + kk;
;                   if (!samp || kk < 1056) pv = *(const u32x4*)(KVg + kr * 2048 + h * 128 + 64 + ec * 8); }
;             } else {
;                 const int j = tid >> 3, ch = tid & 7; const int kk = kt * 64 + j;
;                 if (!samp) { const size_t kr = (size_t)b * 2048 + (size_t)(cch - 2 + kt) * 64 + j;
;                     pk0 = *(const u32x4*)(SP + kr * 1536 + 1024 + kvh * 64 + ch * 8); pv = *(const u32x4*)(SP + kr * 1536 + 1280 + kvh * 64 + ch * 8); }
;                 else if (kk < 128) { pk0 = *(const u32x4*)(KC + ((size_t)b * 128 + kk) * 256 + kvh * 64 + ch * 8); pv = *(const u32x4*)(VC + ((size_t)b * 128 + kk) * 256 + kvh * 64 + ch * 8); }
;                 else if (kk < 160) { const size_t kr = (size_t)NTP + b * 32 + (kk - 128);
;                     pk0 = *(const u32x4*)(SP + kr * 1536 + 1024 + kvh * 64 + ch * 8); pv = *(const u32x4*)(SP + kr * 1536 + 1280 + kvh * 64 + ch * 8); }
;             }
;         };
;         auto stash = [&](int par) {
;             LAS bf16_t* Ks = KsB + par * KVB; LAS bf16_t* VTs = Ks + 64 * QST;
;             if (MLA) {
;                 { const int j = tid / 12, ch = tid % 12; *(LAS u32x4*)(Ks + j * QST + ch * 8) = pk0; }
;                 if (tid < 256) { const int idx = tid + 512; const int j = idx / 12, ch = idx % 12; *(LAS u32x4*)(Ks + j * QST + ch * 8) = pk1; }
;             } else { const int j = tid >> 3, ch = tid & 7; *(LAS u32x4*)(Ks + j * QST + ch * 8) = pk0; }
.LBB0_810:
	s_or_b64 exec, exec, s[2:3]
	v_mov_b32_e32 v99, v187
	s_mov_b32 s33, s69
	s_cmpk_gt_i32 s33, 0x103f
	v_readfirstlane_b32 s0, v99
	s_cbranch_scc1 .LBB0_887
	v_bfe_u32 v0, v99, 4, 2
	v_cmp_eq_u32_e32 vcc, 0, v0
	v_lshlrev_b32_e32 v130, 4, v0
	v_lshlrev_b32_e32 v131, 2, v0
	v_lshlrev_b32_e32 v94, 3, v0
	v_xor_b32_e32 v0, 16, v234
	v_cndmask_b32_e64 v124, 0, 1.0, vcc
	v_lshlrev_b32_e32 v125, 3, v99
	v_cmp_lt_i32_e32 vcc, v0, v235
	s_ashr_i32 s1, s0, 6
	v_ashrrev_i32_e32 v90, 3, v99
	v_and_b32_e32 v92, 56, v125
	s_movk_i32 s2, 0x90
	v_cndmask_b32_e32 v0, v234, v0, vcc
	s_ashr_i32 s48, s0, 7
	s_lshl_b32 s0, s1, 5
	s_and_b32 s49, s1, 3
	v_mul_lo_u32 v126, v90, s2
	v_lshlrev_b32_e32 v2, 1, v92
	v_lshlrev_b32_e32 v132, 2, v0
	v_xor_b32_e32 v0, 32, v234
	v_and_b32_e32 v122, 15, v99
	s_cmp_lt_i32 s1, 4
	s_movk_i32 s1, 0x800
	v_add3_u32 v127, 0, v126, v2
	v_mul_u32_u24_e32 v128, 0x88, v92
	v_lshrrev_b32_e32 v2, 1, v92
	v_and_b32_e32 v2, 24, v2
	v_xor_b32_e32 v2, v2, v90
	v_lshlrev_b32_e32 v2, 1, v2
	v_cmp_lt_i32_e32 vcc, v0, v235
	v_and_or_b32 v123, s0, 32, v122
	v_cmp_gt_i32_e64 s[36:37], s1, v99
	v_add3_u32 v129, 0, v128, v2
	v_or_b32_e32 v2, s0, v122
	v_cndmask_b32_e32 v0, v234, v0, vcc
	v_readlane_b32 s0, v252, 20
	v_add_u32_e32 v3, 0, v130
	v_lshlrev_b32_e32 v133, 2, v0
	v_mov_b32_e32 v95, v1
	v_readlane_b32 s1, v252, 21
	v_mul_lo_u32 v0, v2, s2
	v_and_b32_e32 v2, 7, v99
	s_cselect_b64 s[30:31], -1, 0
	v_ashrrev_i32_e32 v91, 31, v90
	v_lshl_add_u64 v[96:97], s[0:1], 0, v[94:95]
	v_mul_u32_u24_e32 v95, 0x90, v122
	v_or_b32_e32 v134, 16, v122
	v_mul_u32_u24_e32 v135, 0x88, v122
	v_or_b32_e32 v136, 16, v123
	v_lshlrev_b32_e32 v98, 4, v2
	v_mov_b32_e32 v93, v1
	v_add_u32_e32 v137, 0x80, v90
	v_sub_u32_e32 v138, 0, v131
	v_add_u32_e32 v139, v3, v0
	s_mov_b32 s50, s33
	s_branch .LBB0_813

; #define LAS __attribute__((address_space(3)))
; template <bool MLA>
; __device__ __forceinline__ void attn_phase(const Args& a, LAS unsigned char* lds) {
;     ...
;         auto stash = [&](int par) {
;             LAS bf16_t* Ks = KsB + par * KVB; LAS bf16_t* VTs = Ks + 64 * QST;
;             if (MLA) {
;                 { const int j = tid / 12, ch = tid % 12; *(LAS u32x4*)(Ks + j * QST + ch * 8) = pk0; }
;                 if (tid < 256) { const int idx = tid + 512; const int j = idx / 12, ch = idx % 12; *(LAS u32x4*)(Ks + j * QST + ch * 8) = pk1; }
;             } else { const int j = tid >> 3, ch = tid & 7; *(LAS u32x4*)(Ks + j * QST + ch * 8) = pk0; }
;             { const int j = tid >> 3, ec = tid & 7; const unsigned vv[4] = {pv.x, pv.y, pv.z, pv.w};
; #pragma unroll
;               for (int k = 0; k < 4; ++k) { VTs[(ec * 8 + 2 * k) * 68 + j] = (bf16_t)(vv[k] & 0xFFFFu); VTs[(ec * 8 + 2 * k + 1) * 68 + j] = (bf16_t)(vv[k] >> 16); } }
;         };
;         fetch(kt0);
;         stash(0);
;         if (kt0 + 1 < kt1) fetch(kt0 + 1);
; #pragma unroll 1
;         for (int kt = kt0; kt < kt1; ++kt) {
;             __syncthreads();
;             if (kt + 1 < kt1) { stash((kt + 1 - kt0) & 1); if (kt + 2 < kt1) fetch(kt + 2); }
.LBB0_859:
	s_add_i32 s0, s52, s57
	s_cmp_eq_u32 s0, 2
	s_waitcnt lgkmcnt(0)
	s_barrier
	s_cbranch_scc1 .LBB0_861
	s_bitcmp1_b32 s57, 0
	s_cselect_b32 s1, 0, 0x4600
	s_add_i32 s1, s1, 0
	v_add3_u32 v58, s1, v126, v0
	s_waitcnt vmcnt(1)
	ds_write_b128 v58, v[18:21] offset:36864
	v_lshrrev_b32_e32 v58, 1, v92
	v_and_b32_e32 v58, 24, v58
	v_xor_b32_e32 v58, v58, v90
	v_lshlrev_b32_e32 v58, 1, v58
	v_add3_u32 v58, s1, v128, v58
	s_cmp_gt_i32 s0, 0
	s_waitcnt vmcnt(0)
	ds_write_b16 v58, v22 offset:46080
	ds_write_b16_d16_hi v58, v22 offset:46216
	ds_write_b16 v58, v23 offset:46352
	ds_write_b16_d16_hi v58, v23 offset:46488
	ds_write_b16 v58, v24 offset:46624
	ds_write_b16_d16_hi v58, v24 offset:46760
	ds_write_b16 v58, v25 offset:46896
	ds_write_b16_d16_hi v58, v25 offset:47032
	s_cbranch_scc0 .LBB0_869

; #define LAS __attribute__((address_space(3)))
; template <bool MLA>
; __device__ __forceinline__ void attn_phase(const Args& a, LAS unsigned char* lds) {
;     ...
;                 float mx = -INFINITY;
; #pragma unroll
;                 for (int sub = 0; sub < 4; ++sub) mx = fmaxf(fmaxf(fmaxf(mx, sv[sub][0]), fmaxf(sv[sub][1], sv[sub][2])), sv[sub][3]);
;                 mx = fmaxf(mx, __shfl_xor(mx, 16)); mx = fmaxf(mx, __shfl_xor(mx, 32));
;                 const float mn = fmaxf(m[g], mx), alpha = __builtin_amdgcn_exp2f(m[g] - mn); m[g] = mn;
;                 f32x4 ps4 = (f32x4){0.f, 0.f, 0.f, 0.f};
; #pragma unroll
;                 for (int sub = 0; sub < 4; ++sub) {
;                     const f32x4 d = sv[sub] - mn;
;                     const f32x4 pe = (f32x4){__builtin_amdgcn_exp2f(d[0]), __builtin_amdgcn_exp2f(d[1]), __builtin_amdgcn_exp2f(d[2]), __builtin_amdgcn_exp2f(d[3])};
;                     s[g][sub] = pe; ps4 += pe;
;                 }
;                 lsum[g] = lsum[g] * alpha + ((ps4[0] + ps4[1]) + (ps4[2] + ps4[3]));
; #pragma unroll
;                 for (int et = 0; et < 4; ++et) O[g][et] *= alpha;
; #pragma unroll
;                 for (int s2 = 0; s2 < 2; ++s2) {
;                     const unsigned a0 = pk2(s[g][2 * s2][0], s[g][2 * s2][1]), a1 = pk2(s[g][2 * s2][2], s[g][2 * s2][3]), a2 = pk2(s[g][2 * s2 + 1][0], s[g][2 * s2 + 1][1]), a3 = pk2(s[g][2 * s2 + 1][2], s[g][2 * s2 + 1][3]);
;                     const u32x4 pu = (u32x4){a0, a1, a2, a3}; pf[g][s2] = *(const bf16x8*)&pu;
;                 }
;             }
; #pragma unroll
;             for (int s2 = 0; s2 < 2; ++s2)
; #pragma unroll
;                 for (int et = 0; et < 4; ++et) {
;                     const LAS bf16_t* vp = VTs + (et * 16 + r) * 68 + s2 * 32 + quad * 4;
;                     const u32x2 v0 = *(const LAS u32x2*)vp, v1 = *(const LAS u32x2*)(vp + 16);
;                     const u32x4 vu = (u32x4){v0.x, v0.y, v1.x, v1.y};
;                     O[0][et] = __builtin_amdgcn_mfma_f32_16x16x32_bf16(*(const bf16x8*)&vu, pf[0][s2], O[0][et], 0, 0, 0);
;                     O[1][et] = __builtin_amdgcn_mfma_f32_16x16x32_bf16(*(const bf16x8*)&vu, pf[1][s2], O[1][et], 0, 0, 0);
;                 }
.LBB0_867:
	s_waitcnt lgkmcnt(0)
	v_max3_f32 v118, v143, v118, v119
	v_sub_f32_e32 v60, v117, v118
	v_sub_f32_e32 v61, v116, v118
	v_sub_f32_e32 v58, v115, v118
	v_sub_f32_e32 v59, v114, v118
	v_exp_f32_e32 v114, v61
	v_exp_f32_e32 v115, v60
	v_sub_f32_e32 v64, v110, v118
	v_sub_f32_e32 v65, v113, v118
	v_sub_f32_e32 v110, v112, v118
	v_sub_f32_e32 v63, v111, v118
	v_exp_f32_e32 v110, v110
	v_exp_f32_e32 v111, v65
	v_exp_f32_e32 v112, v64
	v_sub_f32_e32 v64, v80, v118
	v_sub_f32_e32 v65, v79, v118
	v_sub_f32_e32 v78, v78, v118
	v_sub_f32_e32 v62, v143, v118
	v_exp_f32_e32 v78, v78
	v_exp_f32_e32 v79, v65
	v_exp_f32_e32 v80, v64
	v_sub_f32_e32 v64, v74, v118
	v_sub_f32_e32 v65, v77, v118
	v_sub_f32_e32 v74, v76, v118
	v_exp_f32_e32 v76, v74
	v_exp_f32_e32 v77, v65
	v_exp_f32_e32 v144, v62
	v_exp_f32_e32 v116, v59
	v_exp_f32_e32 v117, v58
	v_pk_add_f32 v[58:59], v[114:115], 0 op_sel_hi:[1,0]
	v_exp_f32_e32 v113, v63
	v_pk_add_f32 v[58:59], v[110:111], v[58:59]
	v_sub_f32_e32 v63, v81, v118
	v_pk_add_f32 v[58:59], v[78:79], v[58:59]
	v_exp_f32_e32 v81, v63
	v_sub_f32_e32 v63, v75, v118
	v_exp_f32_e32 v120, v64
	v_pk_add_f32 v[58:59], v[76:77], v[58:59]
	v_pk_mul_f32 v[64:65], v[44:45], v[144:145] op_sel_hi:[1,0]
	v_pk_mul_f32 v[44:45], v[56:57], v[144:145] op_sel_hi:[1,0]
	v_cvt_pk_bf16_f32 v56, v76, v77
	v_max3_f32 v75, v86, v89, v88
	v_max3_f32 v76, v68, v71, v70
	v_max3_f32 v75, v75, v82, v85
	v_max3_f32 v76, v76, v66, v73
	v_max3_f32 v75, v75, v87, v84
	v_max3_f32 v76, v76, v69, v72
	s_mov_b32 s0, 0xff800000
	v_max_f32_e32 v75, v75, v83
	v_max3_f32 v75, v75, v76, v67
	ds_bpermute_b32 v76, v132, v75
	v_exp_f32_e32 v121, v63
	v_pk_add_f32 v[60:61], v[116:117], 0 op_sel_hi:[1,0]
	v_pk_mul_f32 v[62:63], v[42:43], v[144:145] op_sel_hi:[1,0]
	v_pk_add_f32 v[60:61], v[112:113], v[60:61]
	s_waitcnt lgkmcnt(0)
	v_max_f32_e32 v75, v75, v76
	ds_bpermute_b32 v76, v133, v75
	v_pk_mul_f32 v[42:43], v[54:55], v[144:145] op_sel_hi:[1,0]
	v_cvt_pk_bf16_f32 v54, v78, v79
	v_pk_add_f32 v[60:61], v[80:81], v[60:61]
	v_cvt_pk_bf16_f32 v55, v80, v81
	s_waitcnt lgkmcnt(0)
	v_max3_f32 v75, v141, v75, v76
	v_sub_f32_e32 v76, v87, v75
	v_sub_f32_e32 v77, v86, v75
	v_sub_f32_e32 v78, v89, v75
	v_sub_f32_e32 v79, v88, v75
	v_exp_f32_e32 v80, v79
	v_exp_f32_e32 v81, v78
	v_exp_f32_e32 v86, v77
	v_exp_f32_e32 v87, v76
	v_sub_f32_e32 v88, v83, v75
	v_sub_f32_e32 v89, v82, v75
	v_sub_f32_e32 v83, v85, v75
	v_sub_f32_e32 v82, v84, v75
	v_pk_add_f32 v[60:61], v[120:121], v[60:61]
	v_exp_f32_e32 v82, v82
	v_exp_f32_e32 v83, v83
	v_exp_f32_e32 v84, v89
	v_exp_f32_e32 v85, v88
	v_sub_f32_e32 v69, v69, v75
	v_sub_f32_e32 v68, v68, v75
	v_sub_f32_e32 v71, v71, v75
	v_sub_f32_e32 v70, v70, v75
	v_add_f32_e32 v58, v58, v59
	v_add_f32_e32 v59, v60, v61
	v_pk_mul_f32 v[60:61], v[48:49], v[144:145] op_sel_hi:[1,0]
	v_cvt_pk_bf16_f32 v48, v110, v111
	v_exp_f32_e32 v88, v70
	v_exp_f32_e32 v89, v71
	v_exp_f32_e32 v110, v68
	v_exp_f32_e32 v111, v69
	v_sub_f32_e32 v67, v67, v75
	v_sub_f32_e32 v66, v66, v75
	v_sub_f32_e32 v73, v73, v75
	v_sub_f32_e32 v72, v72, v75
	v_cvt_pk_bf16_f32 v49, v112, v113
	v_exp_f32_e32 v72, v72
	v_exp_f32_e32 v73, v73
	v_exp_f32_e32 v112, v66
	v_exp_f32_e32 v113, v67
	v_pk_add_f32 v[76:77], v[80:81], 0 op_sel_hi:[1,0]
	v_pk_add_f32 v[78:79], v[86:87], 0 op_sel_hi:[1,0]
	v_pk_add_f32 v[76:77], v[82:83], v[76:77]
	v_pk_add_f32 v[78:79], v[84:85], v[78:79]
	v_add_f32_e32 v74, v58, v59
	v_pk_mul_f32 v[58:59], v[46:47], v[144:145] op_sel_hi:[1,0]
	v_cvt_pk_bf16_f32 v46, v114, v115
	v_sub_f32_e32 v114, v141, v75
	v_pk_add_f32 v[68:69], v[88:89], v[76:77]
	v_pk_add_f32 v[70:71], v[110:111], v[78:79]
	v_pk_add_f32 v[68:69], v[72:73], v[68:69]
	v_pk_add_f32 v[66:67], v[112:113], v[70:71]
	v_exp_f32_e32 v114, v114
	v_pk_mov_b32 v[70:71], v[68:69], v[66:67] op_sel:[1,0]
	v_mov_b32_e32 v69, v67
	v_pk_add_f32 v[66:67], v[70:71], v[68:69]
	v_pk_mul_f32 v[70:71], v[28:29], v[114:115] op_sel_hi:[1,0]
	v_add_f32_e32 v66, v66, v67
	v_add3_u32 v67, s59, v94, v135
	v_xor_b32_e32 v208, 16, v94
	v_add3_u32 v208, s59, v208, v135
	v_pk_mul_f32 v[28:29], v[40:41], v[114:115] op_sel_hi:[1,0]
	v_cvt_pk_bf16_f32 v40, v72, v73
	v_add_u32_e32 v72, 0xb000, v67
	v_pk_mul_f32 v[78:79], v[32:33], v[114:115] op_sel_hi:[1,0]
	v_pk_mul_f32 v[76:77], v[30:31], v[114:115] op_sel_hi:[1,0]
	v_cvt_pk_bf16_f32 v30, v80, v81
	v_cvt_pk_bf16_f32 v32, v82, v83
	ds_read2_b64 v[80:83], v72 offset0:128 offset1:132
	v_cvt_pk_bf16_f32 v47, v116, v117
	v_pk_mul_f32 v[68:69], v[26:27], v[114:115] op_sel_hi:[1,0]
	v_cvt_pk_bf16_f32 v31, v86, v87
	v_cvt_pk_bf16_f32 v33, v84, v85
	v_add_u32_e32 v73, 0xb800, v208
	s_waitcnt lgkmcnt(0)
	v_mfma_f32_16x16x32_bf16 v[62:65], v[80:83], v[46:49], v[62:65]
	v_mul_f32_e64 v26, v38, v114
	v_mul_f32_e64 v27, v39, v114
	v_cvt_pk_bf16_f32 v38, v88, v89
	v_add_u32_e32 v88, 0xc000, v67
	v_mfma_f32_16x16x32_bf16 v[68:71], v[80:83], v[30:33], v[68:71]
	ds_read2_b64 v[80:83], v73 offset0:144 offset1:148
	v_pk_mul_f32 v[52:53], v[52:53], v[144:145] op_sel_hi:[1,0]
	v_pk_mul_f32 v[50:51], v[50:51], v[144:145] op_sel_hi:[1,0]
	s_waitcnt lgkmcnt(0)
	v_mfma_f32_16x16x32_bf16 v[58:61], v[80:83], v[46:49], v[58:61]
	v_mul_f32_e64 v36, v36, v114
	v_mul_f32_e64 v37, v37, v114
	v_pk_mul_f32 v[34:35], v[34:35], v[114:115] op_sel_hi:[1,0]
	v_add_u32_e32 v67, 0xc800, v208
	v_mfma_f32_16x16x32_bf16 v[76:79], v[80:83], v[30:33], v[76:79]
	ds_read2_b64 v[80:83], v88 offset0:164 offset1:160
	v_cvt_pk_bf16_f32 v57, v120, v121
	v_cvt_pk_bf16_f32 v39, v110, v111
	s_waitcnt lgkmcnt(0)
	v_mfma_f32_16x16x32_bf16 v[50:53], v[80:83], v[46:49], v[50:53]
	v_cvt_pk_bf16_f32 v41, v112, v113
	s_mov_b64 s[0:1], 0x8000
	s_add_i32 s57, s57, 1
	v_mfma_f32_16x16x32_bf16 v[34:37], v[80:83], v[30:33], v[34:37]
	ds_read2_b64 v[80:83], v67 offset0:180 offset1:176
	v_lshl_add_u64 v[108:109], v[108:109], 0, s[0:1]
	s_add_i32 s0, s52, s57
	s_waitcnt lgkmcnt(0)
	v_mfma_f32_16x16x32_bf16 v[84:87], v[80:83], v[46:49], v[42:45]
	s_add_i32 s43, s43, 64
	s_add_i32 s0, s0, -1
	s_sub_i32 s56, s56, 64
	v_mfma_f32_16x16x32_bf16 v[80:83], v[80:83], v[30:33], v[26:29]
	ds_read2_b64 v[30:33], v73 offset0:152 offset1:156
	s_add_i32 s58, s58, 1
	v_fmac_f32_e32 v74, v142, v144
	s_waitcnt lgkmcnt(0)
	v_mfma_f32_16x16x32_bf16 v[46:49], v[30:33], v[54:57], v[58:61]
	s_nop 2
	ds_read2_b64 v[58:61], v88 offset0:172 offset1:168
	ds_read2_b64 v[26:29], v72 offset0:136 offset1:140
	v_fmac_f32_e32 v66, v140, v114
	s_waitcnt lgkmcnt(1)
	v_mfma_f32_16x16x32_bf16 v[50:53], v[58:61], v[54:57], v[50:53]
	s_cmp_gt_i32 s0, 1
	v_mfma_f32_16x16x32_bf16 v[34:37], v[58:61], v[38:41], v[34:37]
	ds_read2_b64 v[58:61], v67 offset0:188 offset1:184
	s_waitcnt lgkmcnt(1)
	v_mfma_f32_16x16x32_bf16 v[42:45], v[26:29], v[54:57], v[62:65]
	v_mfma_f32_16x16x32_bf16 v[26:29], v[26:29], v[38:41], v[68:71]
	v_mfma_f32_16x16x32_bf16 v[30:33], v[30:33], v[38:41], v[76:79]
	s_waitcnt lgkmcnt(0)
	v_mfma_f32_16x16x32_bf16 v[54:57], v[58:61], v[54:57], v[84:87]
	v_mfma_f32_16x16x32_bf16 v[38:41], v[58:61], v[38:41], v[80:83]
	s_cbranch_scc1 .LBB0_882
; template <bool MLA>
; __device__ __forceinline__ void attn_phase(const Args& a, LAS unsigned char* lds) {
;     ...
;                 const float mn = fmaxf(m[g], mx), alpha = __builtin_amdgcn_exp2f(m[g] - mn); m[g] = mn;
;                 f32x4 ps4 = (f32x4){0.f, 0.f, 0.f, 0.f};
; #pragma unroll
;                 for (int sub = 0; sub < 4; ++sub) {
;                     const f32x4 d = sv[sub] - mn;
;                     const f32x4 pe = (f32x4){__builtin_amdgcn_exp2f(d[0]), __builtin_amdgcn_exp2f(d[1]), __builtin_amdgcn_exp2f(d[2]), __builtin_amdgcn_exp2f(d[3])};
;                     s[g][sub] = pe; ps4 += pe;
;                 }
;                 lsum[g] = lsum[g] * alpha + ((ps4[0] + ps4[1]) + (ps4[2] + ps4[3]));
	v_mov_b32_e32 v141, v75
	v_mov_b32_e32 v143, v118
	v_mov_b32_e32 v140, v66
	v_mov_b32_e32 v142, v74
	s_branch .LBB0_859
